# FoX tile loop: forget-bias prefetch load no longer waited for where it is issued (raw value into the staging register, scaled at the LDS write), in the fast and slow prefetch paths and the item prolog
# speedup vs baseline: 1.0084x; 1.0084x over previous
; template <int DK, bool BIAS> ...
;     ...
;   auto prefetch = [&](int j, uint4& rk0, uint4& rk1, uint4& rv, float& rfk) {
;     rk0 = kload(64 * j + krow0, kch0);
;     if (NPIECE > 512 && tid + 512 < NPIECE) rk1 = kload(64 * j + krow1, kch1);
;     { const int kg = 64 * j + vrow; rv = make_uint4(0, 0, 0, 0); if (kg < T) rv = *(const uint4*)(Vp + (size_t)(rowb + kg) * ldv + vch * 8); }
;     if (BIAS && tid < 64) { const int kg = 64 * j + tid; rfk = kg < T ? -fc[kg] * LOG2E : 0.f; }
;     ...
;   prefetch(0, rk0A, rk1A, rvA, rfkA); stage(0, rk0A, rk1A, rvA, rfkA);
;   if (nkv > 1) prefetch(1, rk0B, rk1B, rvB, rfkB);
.LBB0_1753:
	s_or_b64 exec, exec, s[8:9]
	v_add_u32_e32 v28, s25, v161
	v_mul_u32_u24_e32 v28, 0x900, v28
	v_lshlrev_b32_e32 v28, 1, v28
	v_mov_b32_e32 v29, v130
	v_lshl_add_u64 v[28:29], s[18:19], 0, v[28:29]
	v_lshl_add_u64 v[28:29], v[34:35], 1, v[28:29]
	global_load_dwordx4 v[28:31], v[28:29], off
	v_mov_b32_e32 v166, 0
	s_and_saveexec_b64 s[8:9], s[6:7]
	s_cbranch_execz .LBB0_1755
	v_lshl_add_u64 v[40:41], v[102:103], 2, s[16:17]
	global_load_dword v166, v[40:41], off offset:256

; template <int DK, bool BIAS> ...
;     ...
;   auto prefetch = [&](int j, uint4& rk0, uint4& rk1, uint4& rv, float& rfk) {
;     rk0 = kload(64 * j + krow0, kch0);
;     if (NPIECE > 512 && tid + 512 < NPIECE) rk1 = kload(64 * j + krow1, kch1);
;     { const int kg = 64 * j + vrow; rv = make_uint4(0, 0, 0, 0); if (kg < T) rv = *(const uint4*)(Vp + (size_t)(rowb + kg) * ldv + vch * 8); }
;     if (BIAS && tid < 64) { const int kg = 64 * j + tid; rfk = kg < T ? -fc[kg] * LOG2E : 0.f; }
;     ...
;     if (j + 2 < nkv) prefetch(j + 2, pk0, pk1, pv, pfk);
.LBB0_1762:
	s_add_i32 s39, s37, -3
	s_cmp_lt_u32 s39, s21
	s_cselect_b64 s[92:93], -1, 0
	s_cmp_ge_u32 s39, s21
	s_cbranch_scc1 .LBB0_1772
	s_add_i32 s0, s38, 0xbf
	s_cmp_lt_i32 s0, s29
	s_cbranch_scc0 .Lpf_fox1_slow
	s_waitcnt vmcnt(0)
	v_add_u32_e32 v16, s38, v160
	v_add_u32_e32 v16, 0x80, v16
	v_mad_i64_i32 v[16:17], s[18:19], v16, s53, v[108:109]
	global_load_dwordx4 v[16:19], v[16:17], off
	v_add_u32_e32 v20, 0x48000, v172
	v_mov_b32_e32 v21, v130
	v_lshl_add_u64 v[20:21], v[20:21], 1, v[110:111]
	global_load_dwordx4 v[20:23], v[20:21], off
	s_and_saveexec_b64 s[0:1], s[6:7]
	s_cbranch_execz .Lpf_fox1_e
	v_add_u32_e32 v64, s38, v102
	v_add_u32_e32 v64, 0x80, v64
	v_ashrrev_i32_e32 v65, 31, v64
	v_lshl_add_u64 v[64:65], v[64:65], 2, s[16:17]
	global_load_dword v162, v[64:65], off

; template <int DK, bool BIAS> ...
;     ...
;   auto prefetch = [&](int j, uint4& rk0, uint4& rk1, uint4& rv, float& rfk) {
;     rk0 = kload(64 * j + krow0, kch0);
;     if (NPIECE > 512 && tid + 512 < NPIECE) rk1 = kload(64 * j + krow1, kch1);
;     { const int kg = 64 * j + vrow; rv = make_uint4(0, 0, 0, 0); if (kg < T) rv = *(const uint4*)(Vp + (size_t)(rowb + kg) * ldv + vch * 8); }
;     if (BIAS && tid < 64) { const int kg = 64 * j + tid; rfk = kg < T ? -fc[kg] * LOG2E : 0.f; }
.LBB0_1767:
	s_or_b64 exec, exec, s[0:1]
	s_and_saveexec_b64 s[0:1], s[6:7]
	s_cbranch_execz .LBB0_1771
	v_add_u32_e32 v64, s38, v102
	v_add_u32_e32 v64, 0x80, v64
	v_cmp_gt_i32_e32 vcc, s29, v64
	v_mov_b32_e32 v162, 0
	s_and_saveexec_b64 s[18:19], vcc
	s_cbranch_execz .LBB0_1770
	v_ashrrev_i32_e32 v65, 31, v64
	v_lshl_add_u64 v[64:65], v[64:65], 2, s[16:17]
	global_load_dword v162, v[64:65], off

; #define LBAR() do { asm volatile("s_waitcnt lgkmcnt(0)" ::: "memory"); __builtin_amdgcn_s_barrier(); asm volatile("" ::: "memory"); } while (0)
; template <int DK, bool BIAS> ...
;     ...
;   auto prefetch = [&](int j, uint4& rk0, uint4& rk1, uint4& rv, float& rfk) {
;     rk0 = kload(64 * j + krow0, kch0);
;     if (NPIECE > 512 && tid + 512 < NPIECE) rk1 = kload(64 * j + krow1, kch1);
;     { const int kg = 64 * j + vrow; rv = make_uint4(0, 0, 0, 0); if (kg < T) rv = *(const uint4*)(Vp + (size_t)(rowb + kg) * ldv + vch * 8); }
;     if (BIAS && tid < 64) { const int kg = 64 * j + tid; rfk = kg < T ? -fc[kg] * LOG2E : 0.f; }
;     ...
;   auto stage = [&](int buf, const uint4& rk0, const uint4& rk1, const uint4& rv, const float& rfk) {
;     *(uint4*)(Ksm + (buf * 64 + krow0) * KST + kch0 * 8) = rk0;
;     if (NPIECE > 512 && tid + 512 < NPIECE) *(uint4*)(Ksm + (buf * 64 + krow1) * KST + kch1 * 8) = rk1;
;     { const unsigned vv[4] = {rv.x, rv.y, rv.z, rv.w};
; #pragma unroll
;       for (int jj = 0; jj < 4; ++jj) { Vtm[(buf * 64 + vch * 8 + 2 * jj) * 72 + vrow] = (bf16_t)(vv[jj] & 0xffffu); Vtm[(buf * 64 + vch * 8 + 2 * jj + 1) * 72 + vrow] = (bf16_t)(vv[jj] >> 16); } }
;     if (BIAS && tid < 64) fkm[buf * 64 + tid] = rfk;
;   };
;     ...
;     if (j + 1 < nkv) stage(buf ^ 1, sk0, sk1, sv, sfk);
;     LBAR();
.LBB0_1778:
	s_or_b64 exec, exec, s[0:1]
	v_cndmask_b32_e64 v64, 0, 1, s[92:93]
	v_cmp_ne_u32_e64 s[0:1], 1, v64
	s_andn2_b64 vcc, exec, s[92:93]
	s_cbranch_vccnz .LBB0_1782
	s_waitcnt vmcnt(1)
	ds_write_b128 v171, v[24:27] offset:9216
	s_waitcnt vmcnt(0)
	ds_write_b16 v164, v28 offset:27648
	ds_write_b16_d16_hi v164, v28 offset:27792
	ds_write_b16 v164, v29 offset:27936
	ds_write_b16_d16_hi v164, v29 offset:28080
	ds_write_b16 v164, v30 offset:28224
	ds_write_b16_d16_hi v164, v30 offset:28368
	ds_write_b16 v164, v31 offset:28512
	ds_write_b16_d16_hi v164, v31 offset:28656
	s_and_saveexec_b64 s[18:19], s[6:7]
	v_mul_f32_e32 v64, 0xbfb8aa3b, v166
	ds_write_b32 v165, v64 offset:37120
	s_or_b64 exec, exec, s[18:19]
.LBB0_1782:
	s_waitcnt lgkmcnt(0)
	s_barrier
	s_and_b64 vcc, exec, s[0:1]
	s_cbranch_vccnz .LBB0_1761
	s_cmp_gt_u32 s37, s21
	s_cbranch_scc1 .LBB0_1793
	s_add_i32 s0, s38, 0xff
	s_cmp_lt_i32 s0, s29
	s_cbranch_scc0 .Lpf_fox2_slow
	s_waitcnt vmcnt(0)
	v_add_u32_e32 v24, s38, v160
	v_add_u32_e32 v24, 0xc0, v24
	v_mad_i64_i32 v[24:25], s[18:19], v24, s53, v[108:109]
	global_load_dwordx4 v[24:27], v[24:25], off
	v_add_u32_e32 v28, 0x6c000, v172
	v_mov_b32_e32 v29, v130
	v_lshl_add_u64 v[28:29], v[28:29], 1, v[110:111]
	global_load_dwordx4 v[28:31], v[28:29], off
	s_and_saveexec_b64 s[0:1], s[6:7]
	s_cbranch_execz .Lpf_fox2_e
	v_add_u32_e32 v64, s38, v102
	v_add_u32_e32 v64, 0xc0, v64
	v_ashrrev_i32_e32 v65, 31, v64
	v_lshl_add_u64 v[64:65], v[64:65], 2, s[16:17]
	global_load_dword v166, v[64:65], off

; template <int DK, bool BIAS> ...
;     ...
;   auto prefetch = [&](int j, uint4& rk0, uint4& rk1, uint4& rv, float& rfk) {
;     rk0 = kload(64 * j + krow0, kch0);
;     if (NPIECE > 512 && tid + 512 < NPIECE) rk1 = kload(64 * j + krow1, kch1);
;     { const int kg = 64 * j + vrow; rv = make_uint4(0, 0, 0, 0); if (kg < T) rv = *(const uint4*)(Vp + (size_t)(rowb + kg) * ldv + vch * 8); }
;     if (BIAS && tid < 64) { const int kg = 64 * j + tid; rfk = kg < T ? -fc[kg] * LOG2E : 0.f; }
.LBB0_1788:
	s_or_b64 exec, exec, s[0:1]
	s_and_saveexec_b64 s[0:1], s[6:7]
	s_cbranch_execz .LBB0_1792
	v_add_u32_e32 v64, s38, v102
	v_add_u32_e32 v64, 0xc0, v64
	v_cmp_gt_i32_e32 vcc, s29, v64
	v_mov_b32_e32 v166, 0
	s_and_saveexec_b64 s[18:19], vcc
	s_cbranch_execz .LBB0_1791
	v_ashrrev_i32_e32 v65, 31, v64
	v_lshl_add_u64 v[64:65], v[64:65], 2, s[16:17]
	global_load_dword v166, v[64:65], off

; template <int DK, bool BIAS> ...
;     ...
;   auto stage = [&](int buf, const uint4& rk0, const uint4& rk1, const uint4& rv, const float& rfk) {
;     *(uint4*)(Ksm + (buf * 64 + krow0) * KST + kch0 * 8) = rk0;
;     if (NPIECE > 512 && tid + 512 < NPIECE) *(uint4*)(Ksm + (buf * 64 + krow1) * KST + kch1 * 8) = rk1;
;     { const unsigned vv[4] = {rv.x, rv.y, rv.z, rv.w};
; #pragma unroll
;       for (int jj = 0; jj < 4; ++jj) { Vtm[(buf * 64 + vch * 8 + 2 * jj) * 72 + vrow] = (bf16_t)(vv[jj] & 0xffffu); Vtm[(buf * 64 + vch * 8 + 2 * jj + 1) * 72 + vrow] = (bf16_t)(vv[jj] >> 16); } }
;     if (BIAS && tid < 64) fkm[buf * 64 + tid] = rfk;
;   };
.LBB0_1799:
	s_or_b64 exec, exec, s[0:1]
	s_waitcnt vmcnt(0)
	ds_write_b128 v163, v[16:19]
	ds_write_b16 v164, v20 offset:18432
	ds_write_b16_d16_hi v164, v20 offset:18576
	ds_write_b16 v164, v21 offset:18720
	ds_write_b16_d16_hi v164, v21 offset:18864
	ds_write_b16 v164, v22 offset:19008
	ds_write_b16_d16_hi v164, v22 offset:19152
	ds_write_b16 v164, v23 offset:19296
	ds_write_b16_d16_hi v164, v23 offset:19440
	s_and_saveexec_b64 s[0:1], s[6:7]
	s_cbranch_execz .LBB0_1760
	v_mul_f32_e32 v64, 0xbfb8aa3b, v162
	ds_write_b32 v165, v64 offset:36864
	s_branch .LBB0_1760
